# P7 epilogue silu with packed f32 mul/add placed in the original scalar slots (transcendentals stay interleaved), temporaries v246-v249
# baseline (speedup 1.0000x reference)
.LBB0_692:
	s_waitcnt vmcnt(0)
	v_fmamk_f32 v198, v198, 0x3a800000, v215
	s_mov_b32 s98, 0xbfb8aa3b
	s_mov_b32 s99, 0xbfb8aa3b
	s_mov_b32 s100, 1.0
	s_mov_b32 s101, 1.0
	v_rsq_f32_e32 v198, v198
	s_cmp_lt_i32 s16, 32
	s_cselect_b32 s0, 2, 0xc2
	s_cmp_lg_u32 s16, 0
	v_pk_fma_f32 v[158:159], v[158:159], v[198:199], v[142:143] op_sel_hi:[1,0,1]
	v_pk_fma_f32 v[156:157], v[156:157], v[198:199], v[140:141] op_sel_hi:[1,0,1]
	v_pk_fma_f32 v[154:155], v[154:155], v[198:199], v[138:139] op_sel_hi:[1,0,1]
	v_pk_fma_f32 v[152:153], v[152:153], v[198:199], v[136:137] op_sel_hi:[1,0,1]
	s_cselect_b32 s46, s0, 0
	s_nop 1
	v_mov_b32_dpp v222, v156 row_ror:1 row_mask:0xf bank_mask:0xf
	v_mov_b32_dpp v226, v156 row_ror:2 row_mask:0xf bank_mask:0xf
	v_mov_b32_dpp v223, v157 row_ror:1 row_mask:0xf bank_mask:0xf
	v_mov_b32_dpp v227, v157 row_ror:2 row_mask:0xf bank_mask:0xf
	v_mov_b32_dpp v224, v158 row_ror:1 row_mask:0xf bank_mask:0xf
	v_mov_b32_dpp v228, v158 row_ror:2 row_mask:0xf bank_mask:0xf
	v_mov_b32_dpp v225, v159 row_ror:1 row_mask:0xf bank_mask:0xf
	v_mov_b32_dpp v229, v159 row_ror:2 row_mask:0xf bank_mask:0xf
	v_mov_b32_dpp v230, v152 row_ror:1 row_mask:0xf bank_mask:0xf
	v_mov_b32_dpp v233, v152 row_ror:2 row_mask:0xf bank_mask:0xf
	v_mov_b32_dpp v231, v153 row_ror:1 row_mask:0xf bank_mask:0xf
	v_mov_b32_dpp v236, v153 row_ror:2 row_mask:0xf bank_mask:0xf
	v_mov_b32_dpp v234, v154 row_ror:1 row_mask:0xf bank_mask:0xf
	v_mov_b32_dpp v239, v154 row_ror:2 row_mask:0xf bank_mask:0xf
	v_mov_b32_dpp v237, v155 row_ror:1 row_mask:0xf bank_mask:0xf
	v_mov_b32_dpp v240, v155 row_ror:2 row_mask:0xf bank_mask:0xf
	v_cmp_le_u32_e64 s[0:1], s46, v200
	s_and_saveexec_b64 s[16:17], s[0:1]
	s_cbranch_execz .LBB0_694
	v_cndmask_b32_e64 v244, v244, v239, s[8:9]
	v_cndmask_b32_e64 v245, v245, v240, s[8:9]
	v_cndmask_b32_e64 v174, v234, v174, s[6:7]
	v_cndmask_b32_e64 v175, v237, v175, s[6:7]
	s_waitcnt vmcnt(4)
	v_pk_mul_f32 v[244:245], v[126:127], v[244:245]
	v_cndmask_b32_e64 v170, v224, v170, s[6:7]
	s_waitcnt vmcnt(2)
	v_pk_fma_f32 v[174:175], v[130:131], v[174:175], v[244:245]
	v_cndmask_b32_e64 v171, v225, v171, s[6:7]
	s_waitcnt vmcnt(0)
	v_pk_fma_f32 v[154:155], v[154:155], v[134:135], v[174:175]
	v_cndmask_b32_e64 v174, v238, v228, s[8:9]
	v_cndmask_b32_e64 v175, v241, v229, s[8:9]
	v_pk_mul_f32 v[174:175], v[122:123], v[174:175]
	v_cndmask_b32_e64 v242, v242, v233, s[8:9]
	v_pk_fma_f32 v[170:171], v[114:115], v[170:171], v[174:175]
	v_cndmask_b32_e64 v243, v243, v236, s[8:9]
	v_pk_fma_f32 v[158:159], v[158:159], v[118:119], v[170:171]
	v_cndmask_b32_e64 v172, v230, v172, s[6:7]
	v_cndmask_b32_e64 v173, v231, v173, s[6:7]
	v_pk_mul_f32 v[242:243], v[124:125], v[242:243]
	v_pk_mul_f32 v[248:249], v[158:159], s[98:99]
	v_exp_f32_e32 v248, v248
	v_pk_fma_f32 v[172:173], v[128:129], v[172:173], v[242:243]
	v_exp_f32_e32 v249, v249
	v_pk_fma_f32 v[152:153], v[152:153], v[132:133], v[172:173]
	v_cndmask_b32_e64 v172, v232, v226, s[8:9]
	v_cndmask_b32_e64 v173, v235, v227, s[8:9]
	v_pk_add_f32 v[248:249], v[248:249], s[100:101]
	v_pk_mul_f32 v[172:173], v[120:121], v[172:173]
	v_cndmask_b32_e64 v168, v222, v168, s[6:7]
	v_cndmask_b32_e64 v169, v223, v169, s[6:7]
	v_pk_fma_f32 v[168:169], v[112:113], v[168:169], v[172:173]
	v_rcp_f32_e32 v248, v248
	v_pk_fma_f32 v[156:157], v[156:157], v[116:117], v[168:169]
	v_rcp_f32_e32 v249, v249
	s_nop 0
	v_pk_mul_f32 v[158:159], v[158:159], v[248:249]
	v_pk_mul_f32 v[246:247], v[156:157], s[98:99]
	v_pk_mul_f32 v[154:155], v[158:159], v[154:155]
	v_exp_f32_e32 v246, v246
	v_exp_f32_e32 v247, v247
	s_nop 0
	v_pk_add_f32 v[246:247], v[246:247], s[100:101]
	v_rcp_f32_e32 v246, v246
	v_rcp_f32_e32 v247, v247
	s_nop 0
	v_pk_mul_f32 v[156:157], v[156:157], v[246:247]
	v_pk_mul_f32 v[152:153], v[156:157], v[152:153]
	v_cvt_pk_bf16_f32 v152, v152, v153
	v_cvt_pk_bf16_f32 v153, v154, v155
	v_mov_b64_e32 v[154:155], s[30:31]
	v_mad_i64_i32 v[154:155], s[18:19], v194, s67, v[154:155]
	v_lshl_add_u64 v[154:155], v[192:193], 1, v[154:155]
	global_store_dwordx2 v[154:155], v[152:153], off
.LBB0_694:
	s_or_b64 exec, exec, s[16:17]
	v_fmamk_f32 v152, v221, 0x3a800000, v215
	v_rsq_f32_e32 v152, v152
	s_nop 0
	v_pk_fma_f32 v[150:151], v[150:151], v[152:153], v[142:143] op_sel_hi:[1,0,1]
	v_pk_fma_f32 v[148:149], v[148:149], v[152:153], v[140:141] op_sel_hi:[1,0,1]
	v_pk_fma_f32 v[146:147], v[146:147], v[152:153], v[138:139] op_sel_hi:[1,0,1]
	v_pk_fma_f32 v[144:145], v[144:145], v[152:153], v[136:137] op_sel_hi:[1,0,1]
	s_nop 1
	v_mov_b32_dpp v153, v148 row_ror:1 row_mask:0xf bank_mask:0xf
	v_mov_b32_dpp v158, v148 row_ror:2 row_mask:0xf bank_mask:0xf
	v_mov_b32_dpp v155, v149 row_ror:1 row_mask:0xf bank_mask:0xf
	v_mov_b32_dpp v159, v149 row_ror:2 row_mask:0xf bank_mask:0xf
	v_mov_b32_dpp v156, v150 row_ror:1 row_mask:0xf bank_mask:0xf
	v_mov_b32_dpp v168, v150 row_ror:2 row_mask:0xf bank_mask:0xf
	v_mov_b32_dpp v157, v151 row_ror:1 row_mask:0xf bank_mask:0xf
	v_mov_b32_dpp v169, v151 row_ror:2 row_mask:0xf bank_mask:0xf
	v_mov_b32_dpp v172, v144 row_ror:1 row_mask:0xf bank_mask:0xf
	v_mov_b32_dpp v174, v144 row_ror:2 row_mask:0xf bank_mask:0xf
	v_mov_b32_dpp v173, v145 row_ror:1 row_mask:0xf bank_mask:0xf
	v_mov_b32_dpp v221, v145 row_ror:2 row_mask:0xf bank_mask:0xf
	v_mov_b32_dpp v175, v146 row_ror:1 row_mask:0xf bank_mask:0xf
	v_mov_b32_dpp v235, v146 row_ror:2 row_mask:0xf bank_mask:0xf
	v_mov_b32_dpp v232, v147 row_ror:1 row_mask:0xf bank_mask:0xf
	v_mov_b32_dpp v238, v147 row_ror:2 row_mask:0xf bank_mask:0xf
	v_or_b32_e32 v203, 16, v200
	v_cmp_le_u32_e64 s[16:17], s46, v203
	v_add_u32_e32 v154, s41, v203
	s_and_saveexec_b64 s[18:19], s[16:17]
	s_cbranch_execz .LBB0_696
	v_cndmask_b32_e64 v170, v233, v174, s[8:9]
	v_cndmask_b32_e64 v171, v236, v221, s[8:9]
	v_cndmask_b32_e64 v230, v172, v230, s[6:7]
	v_cndmask_b32_e64 v231, v173, v231, s[6:7]
	s_waitcnt vmcnt(4)
	v_pk_mul_f32 v[170:171], v[124:125], v[170:171]
	v_cndmask_b32_e64 v224, v156, v224, s[6:7]
	s_waitcnt vmcnt(2)
	v_pk_fma_f32 v[170:171], v[128:129], v[230:231], v[170:171]
	v_cndmask_b32_e64 v225, v157, v225, s[6:7]
	s_waitcnt vmcnt(0)
	v_pk_fma_f32 v[144:145], v[144:145], v[132:133], v[170:171]
	v_cndmask_b32_e64 v170, v226, v158, s[8:9]
	v_cndmask_b32_e64 v171, v227, v159, s[8:9]
	v_cndmask_b32_e64 v226, v228, v168, s[8:9]
	v_cndmask_b32_e64 v227, v229, v169, s[8:9]
	v_pk_mul_f32 v[226:227], v[122:123], v[226:227]
	v_pk_mul_f32 v[170:171], v[120:121], v[170:171]
	v_pk_fma_f32 v[224:225], v[114:115], v[224:225], v[226:227]
	v_cndmask_b32_e64 v222, v153, v222, s[6:7]
	v_pk_fma_f32 v[150:151], v[150:151], v[118:119], v[224:225]
	v_cndmask_b32_e64 v223, v155, v223, s[6:7]
	v_pk_fma_f32 v[170:171], v[112:113], v[222:223], v[170:171]
	v_pk_mul_f32 v[248:249], v[150:151], s[98:99]
	v_cndmask_b32_e64 v242, v239, v235, s[8:9]
	v_exp_f32_e32 v248, v248
	v_exp_f32_e32 v249, v249
	v_cndmask_b32_e64 v243, v240, v238, s[8:9]
	v_pk_add_f32 v[248:249], v[248:249], s[100:101]
	v_cndmask_b32_e64 v236, v175, v234, s[6:7]
	v_cndmask_b32_e64 v237, v232, v237, s[6:7]
	v_pk_mul_f32 v[240:241], v[126:127], v[242:243]
	v_pk_fma_f32 v[148:149], v[148:149], v[116:117], v[170:171]
	v_pk_fma_f32 v[236:237], v[130:131], v[236:237], v[240:241]
	v_rcp_f32_e32 v248, v248
	v_pk_fma_f32 v[146:147], v[146:147], v[134:135], v[236:237]
	v_rcp_f32_e32 v249, v249
	s_nop 0
	v_pk_mul_f32 v[150:151], v[150:151], v[248:249]
	v_pk_mul_f32 v[246:247], v[148:149], s[98:99]
	v_pk_mul_f32 v[146:147], v[150:151], v[146:147]
	v_exp_f32_e32 v246, v246
	v_exp_f32_e32 v247, v247
	s_nop 0
	v_pk_add_f32 v[246:247], v[246:247], s[100:101]
	v_rcp_f32_e32 v246, v246
	v_rcp_f32_e32 v247, v247
	s_nop 0
	v_pk_mul_f32 v[148:149], v[148:149], v[246:247]
	v_pk_mul_f32 v[144:145], v[148:149], v[144:145]
	v_cvt_pk_bf16_f32 v144, v144, v145
	v_cvt_pk_bf16_f32 v145, v146, v147
	v_mov_b64_e32 v[146:147], s[30:31]
	v_mad_i64_i32 v[146:147], s[20:21], v154, s67, v[146:147]
	v_lshl_add_u64 v[146:147], v[192:193], 1, v[146:147]
	global_store_dwordx2 v[146:147], v[144:145], off
.LBB0_696:
	s_or_b64 exec, exec, s[18:19]
	v_fmamk_f32 v144, v220, 0x3a800000, v215
	v_rsq_f32_e32 v144, v144
	s_nop 0
	v_pk_fma_f32 v[110:111], v[110:111], v[144:145], v[142:143] op_sel_hi:[1,0,1]
	v_pk_fma_f32 v[108:109], v[108:109], v[144:145], v[140:141] op_sel_hi:[1,0,1]
	v_pk_fma_f32 v[102:103], v[102:103], v[144:145], v[138:139] op_sel_hi:[1,0,1]
	v_pk_fma_f32 v[100:101], v[100:101], v[144:145], v[136:137] op_sel_hi:[1,0,1]
	s_nop 1
	v_mov_b32_dpp v145, v108 row_ror:1 row_mask:0xf bank_mask:0xf
	v_mov_b32_dpp v150, v108 row_ror:2 row_mask:0xf bank_mask:0xf
	v_mov_b32_dpp v146, v109 row_ror:1 row_mask:0xf bank_mask:0xf
	v_mov_b32_dpp v151, v109 row_ror:2 row_mask:0xf bank_mask:0xf
	v_mov_b32_dpp v148, v110 row_ror:1 row_mask:0xf bank_mask:0xf
	v_mov_b32_dpp v170, v110 row_ror:2 row_mask:0xf bank_mask:0xf
	v_mov_b32_dpp v149, v111 row_ror:1 row_mask:0xf bank_mask:0xf
	v_mov_b32_dpp v171, v111 row_ror:2 row_mask:0xf bank_mask:0xf
	v_mov_b32_dpp v220, v100 row_ror:1 row_mask:0xf bank_mask:0xf
	v_mov_b32_dpp v223, v100 row_ror:2 row_mask:0xf bank_mask:0xf
	v_mov_b32_dpp v222, v101 row_ror:1 row_mask:0xf bank_mask:0xf
	v_mov_b32_dpp v225, v101 row_ror:2 row_mask:0xf bank_mask:0xf
	v_mov_b32_dpp v224, v102 row_ror:1 row_mask:0xf bank_mask:0xf
	v_mov_b32_dpp v227, v102 row_ror:2 row_mask:0xf bank_mask:0xf
	v_mov_b32_dpp v226, v103 row_ror:1 row_mask:0xf bank_mask:0xf
	v_mov_b32_dpp v228, v103 row_ror:2 row_mask:0xf bank_mask:0xf
	v_or_b32_e32 v204, 32, v200
	v_cmp_le_u32_e64 s[18:19], s46, v204
	v_add_u32_e32 v147, s41, v204
	s_and_saveexec_b64 s[20:21], s[18:19]
	s_cbranch_execz .LBB0_698
	v_cndmask_b32_e64 v168, v168, v170, s[8:9]
	v_cndmask_b32_e64 v169, v169, v171, s[8:9]
	s_waitcnt vmcnt(5)
	v_pk_mul_f32 v[168:169], v[122:123], v[168:169]
	v_cndmask_b32_e64 v156, v148, v156, s[6:7]
	v_cndmask_b32_e64 v157, v149, v157, s[6:7]
	s_waitcnt vmcnt(3)
	v_pk_fma_f32 v[156:157], v[114:115], v[156:157], v[168:169]
	v_cndmask_b32_e64 v234, v235, v227, s[8:9]
	s_waitcnt vmcnt(1)
	v_pk_fma_f32 v[110:111], v[110:111], v[118:119], v[156:157]
	v_cndmask_b32_e64 v157, v146, v155, s[6:7]
	v_cndmask_b32_e64 v156, v145, v153, s[6:7]
	v_pk_mul_f32 v[248:249], v[110:111], s[98:99]
	v_cndmask_b32_e64 v235, v238, v228, s[8:9]
	v_exp_f32_e32 v248, v248
	v_exp_f32_e32 v249, v249
	v_cndmask_b32_e64 v158, v158, v150, s[8:9]
	v_cndmask_b32_e64 v159, v159, v151, s[8:9]
	v_pk_add_f32 v[248:249], v[248:249], s[100:101]
	v_cndmask_b32_e64 v230, v174, v223, s[8:9]
	v_cndmask_b32_e64 v174, v224, v175, s[6:7]
	v_cndmask_b32_e64 v175, v226, v232, s[6:7]
	v_pk_mul_f32 v[232:233], v[126:127], v[234:235]
	v_pk_mul_f32 v[158:159], v[120:121], v[158:159]
	v_pk_fma_f32 v[174:175], v[130:131], v[174:175], v[232:233]
	v_pk_fma_f32 v[156:157], v[112:113], v[156:157], v[158:159]
	s_waitcnt vmcnt(0)
	v_pk_fma_f32 v[102:103], v[102:103], v[134:135], v[174:175]
	v_pk_fma_f32 v[108:109], v[108:109], v[116:117], v[156:157]
	v_rcp_f32_e32 v248, v248
	v_rcp_f32_e32 v249, v249
	s_nop 0
	v_pk_mul_f32 v[110:111], v[110:111], v[248:249]
	v_pk_mul_f32 v[246:247], v[108:109], s[98:99]
	v_pk_mul_f32 v[102:103], v[110:111], v[102:103]
	v_exp_f32_e32 v246, v246
	v_exp_f32_e32 v247, v247
	v_cndmask_b32_e64 v231, v221, v225, s[8:9]
	v_pk_add_f32 v[246:247], v[246:247], s[100:101]
	v_rcp_f32_e32 v246, v246
	v_rcp_f32_e32 v247, v247
	s_nop 0
	v_pk_mul_f32 v[108:109], v[108:109], v[246:247]
	v_cndmask_b32_e64 v172, v220, v172, s[6:7]
	v_cndmask_b32_e64 v173, v222, v173, s[6:7]
	v_pk_mul_f32 v[230:231], v[124:125], v[230:231]
	v_pk_fma_f32 v[172:173], v[128:129], v[172:173], v[230:231]
	v_pk_fma_f32 v[100:101], v[100:101], v[132:133], v[172:173]
	v_pk_mul_f32 v[100:101], v[108:109], v[100:101]
	v_cvt_pk_bf16_f32 v100, v100, v101
	v_cvt_pk_bf16_f32 v101, v102, v103
	v_mov_b64_e32 v[102:103], s[30:31]
	v_mad_i64_i32 v[102:103], s[22:23], v147, s67, v[102:103]
	v_lshl_add_u64 v[102:103], v[192:193], 1, v[102:103]
	global_store_dwordx2 v[102:103], v[100:101], off
.LBB0_698:
	s_or_b64 exec, exec, s[20:21]
	s_nop 1
	v_mov_b32_dpp v100, v160 row_ror:1 row_mask:0xf bank_mask:0xf
	v_mov_b32_dpp v108, v160 row_ror:2 row_mask:0xf bank_mask:0xf
	v_mov_b32_dpp v101, v161 row_ror:1 row_mask:0xf bank_mask:0xf
	v_mov_b32_dpp v110, v161 row_ror:2 row_mask:0xf bank_mask:0xf
	v_mov_b32_dpp v102, v162 row_ror:1 row_mask:0xf bank_mask:0xf
	v_mov_b32_dpp v111, v162 row_ror:2 row_mask:0xf bank_mask:0xf
	v_mov_b32_dpp v103, v163 row_ror:1 row_mask:0xf bank_mask:0xf
	v_mov_b32_dpp v153, v163 row_ror:2 row_mask:0xf bank_mask:0xf
	v_mov_b32_dpp v155, v164 row_ror:1 row_mask:0xf bank_mask:0xf
	v_mov_b32_dpp v157, v164 row_ror:2 row_mask:0xf bank_mask:0xf
	v_mov_b32_dpp v156, v165 row_ror:1 row_mask:0xf bank_mask:0xf
	v_mov_b32_dpp v159, v165 row_ror:2 row_mask:0xf bank_mask:0xf
	v_mov_b32_dpp v158, v166 row_ror:1 row_mask:0xf bank_mask:0xf
	v_mov_b32_dpp v169, v166 row_ror:2 row_mask:0xf bank_mask:0xf
	v_mov_b32_dpp v168, v167 row_ror:1 row_mask:0xf bank_mask:0xf
	v_mov_b32_dpp v172, v167 row_ror:2 row_mask:0xf bank_mask:0xf
	v_or_b32_e32 v205, 48, v200
	v_cmp_le_u32_e64 s[20:21], s46, v205
	v_add_u32_e32 v109, s41, v205
	s_and_saveexec_b64 s[22:23], s[20:21]
	s_cbranch_execz .LBB0_700
	v_cndmask_b32_e64 v151, v151, v110, s[8:9]
	v_cndmask_b32_e64 v110, v170, v111, s[8:9]
	v_cndmask_b32_e64 v111, v171, v153, s[8:9]
	s_waitcnt vmcnt(5)
	v_pk_mul_f32 v[110:111], v[122:123], v[110:111]
	v_cndmask_b32_e64 v102, v102, v148, s[6:7]
	v_cndmask_b32_e64 v103, v103, v149, s[6:7]
	s_waitcnt vmcnt(3)
	v_pk_fma_f32 v[102:103], v[114:115], v[102:103], v[110:111]
	v_cndmask_b32_e64 v150, v150, v108, s[8:9]
	s_waitcnt vmcnt(1)
	v_pk_fma_f32 v[102:103], v[162:163], v[118:119], v[102:103]
	v_pk_mul_f32 v[150:151], v[120:121], v[150:151]
	v_pk_mul_f32 v[248:249], v[102:103], s[98:99]
	v_exp_f32_e32 v248, v248
	v_cndmask_b32_e64 v100, v100, v145, s[6:7]
	v_exp_f32_e32 v249, v249
	s_nop 0
	v_pk_add_f32 v[248:249], v[248:249], s[100:101]
	v_cndmask_b32_e64 v101, v101, v146, s[6:7]
	v_pk_fma_f32 v[100:101], v[112:113], v[100:101], v[150:151]
	v_cndmask_b32_e64 v174, v223, v157, s[8:9]
	v_pk_fma_f32 v[100:101], v[160:161], v[116:117], v[100:101]
	v_rcp_f32_e32 v248, v248
	v_rcp_f32_e32 v249, v249
	v_pk_mul_f32 v[246:247], v[100:101], s[98:99]
	s_nop 0
	v_pk_mul_f32 v[102:103], v[102:103], v[248:249]
	v_exp_f32_e32 v246, v246
	v_exp_f32_e32 v247, v247
	v_cndmask_b32_e64 v175, v225, v159, s[8:9]
	v_pk_add_f32 v[246:247], v[246:247], s[100:101]
	v_rcp_f32_e32 v246, v246
	v_rcp_f32_e32 v247, v247
	s_nop 0
	v_pk_mul_f32 v[100:101], v[100:101], v[246:247]
	v_cndmask_b32_e64 v230, v227, v169, s[8:9]
	v_cndmask_b32_e64 v231, v228, v172, s[8:9]
	v_cndmask_b32_e64 v172, v155, v220, s[6:7]
	v_cndmask_b32_e64 v173, v156, v222, s[6:7]
	v_cndmask_b32_e64 v156, v158, v224, s[6:7]
	v_cndmask_b32_e64 v157, v168, v226, s[6:7]
	v_pk_mul_f32 v[158:159], v[124:125], v[174:175]
	v_pk_mul_f32 v[168:169], v[126:127], v[230:231]
	v_pk_fma_f32 v[158:159], v[128:129], v[172:173], v[158:159]
	v_pk_fma_f32 v[156:157], v[130:131], v[156:157], v[168:169]
	s_waitcnt vmcnt(0)
	v_pk_fma_f32 v[158:159], v[164:165], v[132:133], v[158:159]
	v_pk_fma_f32 v[156:157], v[166:167], v[134:135], v[156:157]
	v_pk_mul_f32 v[100:101], v[100:101], v[158:159]
	v_pk_mul_f32 v[102:103], v[102:103], v[156:157]
	v_cvt_pk_bf16_f32 v100, v100, v101
	v_cvt_pk_bf16_f32 v101, v102, v103
	v_mov_b64_e32 v[102:103], s[30:31]
	v_mad_i64_i32 v[102:103], s[24:25], v109, s67, v[102:103]
	v_lshl_add_u64 v[102:103], v[192:193], 1, v[102:103]
	global_store_dwordx2 v[102:103], v[100:101], off
.LBB0_700:
	s_or_b64 exec, exec, s[22:23]
	v_fmamk_f32 v100, v219, 0x3a800000, v215
	v_rsq_f32_e32 v108, v100
	s_nop 0
	v_pk_fma_f32 v[94:95], v[94:95], v[108:109], v[142:143] op_sel_hi:[1,0,1]
	v_pk_fma_f32 v[92:93], v[92:93], v[108:109], v[140:141] op_sel_hi:[1,0,1]
	v_pk_fma_f32 v[90:91], v[90:91], v[108:109], v[138:139] op_sel_hi:[1,0,1]
	v_pk_fma_f32 v[88:89], v[88:89], v[108:109], v[136:137] op_sel_hi:[1,0,1]
	s_nop 1
	v_mov_b32_dpp v100, v92 row_ror:1 row_mask:0xf bank_mask:0xf
	v_mov_b32_dpp v110, v92 row_ror:2 row_mask:0xf bank_mask:0xf
	v_mov_b32_dpp v101, v93 row_ror:1 row_mask:0xf bank_mask:0xf
	v_mov_b32_dpp v145, v93 row_ror:2 row_mask:0xf bank_mask:0xf
	v_mov_b32_dpp v102, v94 row_ror:1 row_mask:0xf bank_mask:0xf
	v_mov_b32_dpp v150, v94 row_ror:2 row_mask:0xf bank_mask:0xf
	v_mov_b32_dpp v103, v95 row_ror:1 row_mask:0xf bank_mask:0xf
	v_mov_b32_dpp v151, v95 row_ror:2 row_mask:0xf bank_mask:0xf
	v_mov_b32_dpp v153, v88 row_ror:1 row_mask:0xf bank_mask:0xf
	v_mov_b32_dpp v156, v88 row_ror:2 row_mask:0xf bank_mask:0xf
	v_mov_b32_dpp v155, v89 row_ror:1 row_mask:0xf bank_mask:0xf
	v_mov_b32_dpp v158, v89 row_ror:2 row_mask:0xf bank_mask:0xf
	v_mov_b32_dpp v157, v90 row_ror:1 row_mask:0xf bank_mask:0xf
	v_mov_b32_dpp v160, v90 row_ror:2 row_mask:0xf bank_mask:0xf
	v_mov_b32_dpp v159, v91 row_ror:1 row_mask:0xf bank_mask:0xf
	v_mov_b32_dpp v161, v91 row_ror:2 row_mask:0xf bank_mask:0xf
	v_add_u32_e32 v206, 0x80, v200
	v_cmp_le_u32_e64 s[22:23], s46, v206
	v_add_u32_e32 v149, s64, v202
	v_add_u32_e32 v111, s41, v206
	s_and_saveexec_b64 s[24:25], s[22:23]
	s_cbranch_execz .LBB0_702
	ds_read_b128 v[162:165], v149 offset:288
	ds_read_b128 v[166:169], v149 offset:32
	ds_read_b128 v[170:173], v149
	ds_read_b128 v[220:223], v149 offset:256
	s_waitcnt lgkmcnt(2)
	v_cndmask_b32_e64 v146, v165, v169, s[6:7]
	v_cndmask_b32_e64 v148, v164, v168, s[6:7]
	v_cndmask_b32_e64 v168, v148, v160, s[8:9]
	v_cndmask_b32_e64 v169, v146, v161, s[8:9]
	v_cndmask_b32_e64 v167, v163, v167, s[6:7]
	v_cndmask_b32_e64 v166, v162, v166, s[6:7]
	v_cndmask_b32_e64 v164, v157, v164, s[6:7]
	v_cndmask_b32_e64 v165, v159, v165, s[6:7]
	s_waitcnt vmcnt(4)
	v_pk_mul_f32 v[168:169], v[126:127], v[168:169]
	v_cndmask_b32_e64 v166, v166, v156, s[8:9]
	v_cndmask_b32_e64 v167, v167, v158, s[8:9]
	s_waitcnt vmcnt(2)
	v_pk_fma_f32 v[164:165], v[130:131], v[164:165], v[168:169]
	s_waitcnt lgkmcnt(0)
	v_cndmask_b32_e64 v146, v223, v173, s[6:7]
	v_cndmask_b32_e64 v148, v222, v172, s[6:7]
	v_cndmask_b32_e64 v162, v153, v162, s[6:7]
	v_cndmask_b32_e64 v163, v155, v163, s[6:7]
	v_pk_mul_f32 v[166:167], v[124:125], v[166:167]
	s_waitcnt vmcnt(0)
	v_pk_fma_f32 v[90:91], v[90:91], v[134:135], v[164:165]
	v_cndmask_b32_e64 v164, v148, v150, s[8:9]
	v_cndmask_b32_e64 v165, v146, v151, s[8:9]
	v_pk_fma_f32 v[162:163], v[128:129], v[162:163], v[166:167]
	v_pk_mul_f32 v[164:165], v[122:123], v[164:165]
	v_cndmask_b32_e64 v166, v102, v222, s[6:7]
	v_cndmask_b32_e64 v167, v103, v223, s[6:7]
	v_pk_fma_f32 v[164:165], v[114:115], v[166:167], v[164:165]
	v_pk_fma_f32 v[88:89], v[88:89], v[132:133], v[162:163]
	v_pk_fma_f32 v[94:95], v[94:95], v[118:119], v[164:165]
	v_cndmask_b32_e64 v163, v221, v171, s[6:7]
	v_cndmask_b32_e64 v162, v220, v170, s[6:7]
	v_pk_mul_f32 v[248:249], v[94:95], s[98:99]
	v_cndmask_b32_e64 v162, v162, v110, s[8:9]
	v_exp_f32_e32 v248, v248
	v_exp_f32_e32 v249, v249
	v_cndmask_b32_e64 v163, v163, v145, s[8:9]
	v_pk_add_f32 v[248:249], v[248:249], s[100:101]
	v_pk_mul_f32 v[162:163], v[120:121], v[162:163]
	v_cndmask_b32_e64 v164, v100, v220, s[6:7]
	v_cndmask_b32_e64 v165, v101, v221, s[6:7]
	v_pk_fma_f32 v[162:163], v[112:113], v[164:165], v[162:163]
	v_rcp_f32_e32 v248, v248
	v_pk_fma_f32 v[92:93], v[92:93], v[116:117], v[162:163]
	v_rcp_f32_e32 v249, v249
	s_nop 0
	v_pk_mul_f32 v[94:95], v[94:95], v[248:249]
	v_pk_mul_f32 v[246:247], v[92:93], s[98:99]
	v_pk_mul_f32 v[90:91], v[94:95], v[90:91]
	v_exp_f32_e32 v246, v246
	v_exp_f32_e32 v247, v247
	s_nop 0
	v_pk_add_f32 v[246:247], v[246:247], s[100:101]
	v_rcp_f32_e32 v246, v246
	v_rcp_f32_e32 v247, v247
	s_nop 0
	v_pk_mul_f32 v[92:93], v[92:93], v[246:247]
	v_pk_mul_f32 v[88:89], v[92:93], v[88:89]
	v_cvt_pk_bf16_f32 v88, v88, v89
	v_cvt_pk_bf16_f32 v89, v90, v91
	v_mov_b64_e32 v[90:91], s[30:31]
	v_mad_i64_i32 v[90:91], s[26:27], v111, s67, v[90:91]
	v_lshl_add_u64 v[90:91], v[192:193], 1, v[90:91]
	global_store_dwordx2 v[90:91], v[88:89], off
.LBB0_702:
	s_or_b64 exec, exec, s[24:25]
	v_fmamk_f32 v88, v218, 0x3a800000, v215
	v_rsq_f32_e32 v146, v88
	s_nop 0
	v_pk_fma_f32 v[86:87], v[86:87], v[146:147], v[142:143] op_sel_hi:[1,0,1]
	v_pk_fma_f32 v[84:85], v[84:85], v[146:147], v[140:141] op_sel_hi:[1,0,1]
	v_pk_fma_f32 v[82:83], v[82:83], v[146:147], v[138:139] op_sel_hi:[1,0,1]
	v_pk_fma_f32 v[80:81], v[80:81], v[146:147], v[136:137] op_sel_hi:[1,0,1]
	s_nop 1
	v_mov_b32_dpp v88, v84 row_ror:1 row_mask:0xf bank_mask:0xf
	v_mov_b32_dpp v92, v84 row_ror:2 row_mask:0xf bank_mask:0xf
	v_mov_b32_dpp v89, v85 row_ror:1 row_mask:0xf bank_mask:0xf
	v_mov_b32_dpp v93, v85 row_ror:2 row_mask:0xf bank_mask:0xf
	v_mov_b32_dpp v90, v86 row_ror:1 row_mask:0xf bank_mask:0xf
	v_mov_b32_dpp v94, v86 row_ror:2 row_mask:0xf bank_mask:0xf
	v_mov_b32_dpp v91, v87 row_ror:1 row_mask:0xf bank_mask:0xf
	v_mov_b32_dpp v95, v87 row_ror:2 row_mask:0xf bank_mask:0xf
	v_mov_b32_dpp v162, v80 row_ror:1 row_mask:0xf bank_mask:0xf
	v_mov_b32_dpp v164, v80 row_ror:2 row_mask:0xf bank_mask:0xf
	v_mov_b32_dpp v163, v81 row_ror:1 row_mask:0xf bank_mask:0xf
	v_mov_b32_dpp v166, v81 row_ror:2 row_mask:0xf bank_mask:0xf
	v_mov_b32_dpp v165, v82 row_ror:1 row_mask:0xf bank_mask:0xf
	v_mov_b32_dpp v168, v82 row_ror:2 row_mask:0xf bank_mask:0xf
	v_mov_b32_dpp v167, v83 row_ror:1 row_mask:0xf bank_mask:0xf
	v_mov_b32_dpp v169, v83 row_ror:2 row_mask:0xf bank_mask:0xf
	v_add_u32_e32 v207, 0x90, v200
	v_cmp_le_u32_e64 s[24:25], s46, v207
	v_add_u32_e32 v148, s41, v207
	s_and_saveexec_b64 s[26:27], s[24:25]
	s_cbranch_execz .LBB0_704
	v_cndmask_b32_e64 v150, v150, v94, s[8:9]
	v_cndmask_b32_e64 v151, v151, v95, s[8:9]
	s_waitcnt vmcnt(5)
	v_pk_mul_f32 v[150:151], v[122:123], v[150:151]
	v_cndmask_b32_e64 v102, v90, v102, s[6:7]
	v_cndmask_b32_e64 v103, v91, v103, s[6:7]
	s_waitcnt vmcnt(3)
	v_pk_fma_f32 v[102:103], v[114:115], v[102:103], v[150:151]
	v_cndmask_b32_e64 v160, v160, v168, s[8:9]
	s_waitcnt vmcnt(1)
	v_pk_fma_f32 v[86:87], v[86:87], v[118:119], v[102:103]
	v_cndmask_b32_e64 v161, v161, v169, s[8:9]
	v_cndmask_b32_e64 v170, v156, v164, s[8:9]
	v_cndmask_b32_e64 v156, v165, v157, s[6:7]
	v_cndmask_b32_e64 v157, v167, v159, s[6:7]
	v_pk_mul_f32 v[160:161], v[126:127], v[160:161]
	v_pk_fma_f32 v[156:157], v[130:131], v[156:157], v[160:161]
	v_pk_mul_f32 v[248:249], v[86:87], s[98:99]
	s_waitcnt vmcnt(0)
	v_pk_fma_f32 v[82:83], v[82:83], v[134:135], v[156:157]
	v_cndmask_b32_e64 v156, v110, v92, s[8:9]
	v_cndmask_b32_e64 v157, v145, v93, s[8:9]
	v_exp_f32_e32 v248, v248
	v_pk_mul_f32 v[156:157], v[120:121], v[156:157]
	v_cndmask_b32_e64 v100, v88, v100, s[6:7]
	v_cndmask_b32_e64 v101, v89, v101, s[6:7]
	v_pk_fma_f32 v[100:101], v[112:113], v[100:101], v[156:157]
	v_exp_f32_e32 v249, v249
	v_pk_fma_f32 v[84:85], v[84:85], v[116:117], v[100:101]
	v_pk_add_f32 v[248:249], v[248:249], s[100:101]
	v_rcp_f32_e32 v248, v248
	v_pk_mul_f32 v[246:247], v[84:85], s[98:99]
	v_rcp_f32_e32 v249, v249
	v_exp_f32_e32 v246, v246
	v_exp_f32_e32 v247, v247
	v_cndmask_b32_e64 v171, v158, v166, s[8:9]
	v_pk_mul_f32 v[86:87], v[86:87], v[248:249]
	v_pk_add_f32 v[246:247], v[246:247], s[100:101]
	v_rcp_f32_e32 v246, v246
	v_rcp_f32_e32 v247, v247
	s_nop 0
	v_pk_mul_f32 v[84:85], v[84:85], v[246:247]
	v_cndmask_b32_e64 v172, v162, v153, s[6:7]
	v_cndmask_b32_e64 v173, v163, v155, s[6:7]
	v_pk_mul_f32 v[158:159], v[124:125], v[170:171]
	v_pk_fma_f32 v[158:159], v[128:129], v[172:173], v[158:159]
	v_pk_fma_f32 v[80:81], v[80:81], v[132:133], v[158:159]
	v_pk_mul_f32 v[82:83], v[86:87], v[82:83]
	v_pk_mul_f32 v[80:81], v[84:85], v[80:81]
	v_cvt_pk_bf16_f32 v80, v80, v81
	v_cvt_pk_bf16_f32 v81, v82, v83
	v_mov_b64_e32 v[82:83], s[30:31]
	v_mad_i64_i32 v[82:83], s[28:29], v148, s67, v[82:83]
	v_lshl_add_u64 v[82:83], v[192:193], 1, v[82:83]
	global_store_dwordx2 v[82:83], v[80:81], off
.LBB0_704:
	s_or_b64 exec, exec, s[26:27]
	v_fmamk_f32 v80, v199, 0x3a800000, v215
	v_rsq_f32_e32 v110, v80
	s_nop 0
	v_pk_fma_f32 v[78:79], v[78:79], v[110:111], v[142:143] op_sel_hi:[1,0,1]
	v_pk_fma_f32 v[76:77], v[76:77], v[110:111], v[140:141] op_sel_hi:[1,0,1]
	v_pk_fma_f32 v[74:75], v[74:75], v[110:111], v[138:139] op_sel_hi:[1,0,1]
	v_pk_fma_f32 v[72:73], v[72:73], v[110:111], v[136:137] op_sel_hi:[1,0,1]
	s_nop 1
	v_mov_b32_dpp v80, v76 row_ror:1 row_mask:0xf bank_mask:0xf
	v_mov_b32_dpp v84, v76 row_ror:2 row_mask:0xf bank_mask:0xf
	v_mov_b32_dpp v81, v77 row_ror:1 row_mask:0xf bank_mask:0xf
	v_mov_b32_dpp v85, v77 row_ror:2 row_mask:0xf bank_mask:0xf
	v_mov_b32_dpp v82, v78 row_ror:1 row_mask:0xf bank_mask:0xf
	v_mov_b32_dpp v86, v78 row_ror:2 row_mask:0xf bank_mask:0xf
	v_mov_b32_dpp v83, v79 row_ror:1 row_mask:0xf bank_mask:0xf
	v_mov_b32_dpp v87, v79 row_ror:2 row_mask:0xf bank_mask:0xf
	v_mov_b32_dpp v100, v72 row_ror:1 row_mask:0xf bank_mask:0xf
	v_mov_b32_dpp v102, v72 row_ror:2 row_mask:0xf bank_mask:0xf
	v_mov_b32_dpp v101, v73 row_ror:1 row_mask:0xf bank_mask:0xf
	v_mov_b32_dpp v138, v73 row_ror:2 row_mask:0xf bank_mask:0xf
	v_mov_b32_dpp v103, v74 row_ror:1 row_mask:0xf bank_mask:0xf
	v_mov_b32_dpp v140, v74 row_ror:2 row_mask:0xf bank_mask:0xf
	v_mov_b32_dpp v139, v75 row_ror:1 row_mask:0xf bank_mask:0xf
	v_mov_b32_dpp v141, v75 row_ror:2 row_mask:0xf bank_mask:0xf
	v_add_u32_e32 v209, 0xa0, v200
	v_cmp_le_u32_e64 s[26:27], s46, v209
	v_add_u32_e32 v136, s41, v209
	s_and_saveexec_b64 s[28:29], s[26:27]
	s_cbranch_execz .LBB0_706
	v_cndmask_b32_e64 v94, v94, v86, s[8:9]
	v_cndmask_b32_e64 v95, v95, v87, s[8:9]
	s_waitcnt vmcnt(5)
	v_pk_mul_f32 v[94:95], v[122:123], v[94:95]
	v_cndmask_b32_e64 v90, v82, v90, s[6:7]
	v_cndmask_b32_e64 v91, v83, v91, s[6:7]
	s_waitcnt vmcnt(3)
	v_pk_fma_f32 v[90:91], v[114:115], v[90:91], v[94:95]
	v_cndmask_b32_e64 v150, v168, v140, s[8:9]
	s_waitcnt vmcnt(1)
	v_pk_fma_f32 v[78:79], v[78:79], v[118:119], v[90:91]
	v_cndmask_b32_e64 v151, v169, v141, s[8:9]
	v_pk_mul_f32 v[248:249], v[78:79], s[98:99]
	v_cndmask_b32_e64 v92, v92, v84, s[8:9]
	v_cndmask_b32_e64 v93, v93, v85, s[8:9]
	v_exp_f32_e32 v248, v248
	v_exp_f32_e32 v249, v249
	s_nop 0
	v_pk_add_f32 v[248:249], v[248:249], s[100:101]
	v_cndmask_b32_e64 v158, v103, v165, s[6:7]
	v_cndmask_b32_e64 v159, v139, v167, s[6:7]
	v_pk_mul_f32 v[150:151], v[126:127], v[150:151]
	v_pk_mul_f32 v[92:93], v[120:121], v[92:93]
	v_cndmask_b32_e64 v88, v80, v88, s[6:7]
	v_cndmask_b32_e64 v89, v81, v89, s[6:7]
	v_pk_fma_f32 v[150:151], v[130:131], v[158:159], v[150:151]
	v_pk_fma_f32 v[88:89], v[112:113], v[88:89], v[92:93]
	s_waitcnt vmcnt(0)
	v_pk_fma_f32 v[74:75], v[74:75], v[134:135], v[150:151]
	v_pk_fma_f32 v[76:77], v[76:77], v[116:117], v[88:89]
	v_rcp_f32_e32 v248, v248
	v_rcp_f32_e32 v249, v249
	s_nop 0
	v_pk_mul_f32 v[78:79], v[78:79], v[248:249]
	v_pk_mul_f32 v[246:247], v[76:77], s[98:99]
	v_pk_mul_f32 v[74:75], v[78:79], v[74:75]
	v_exp_f32_e32 v246, v246
	v_exp_f32_e32 v247, v247
	v_cndmask_b32_e64 v142, v164, v102, s[8:9]
	v_pk_add_f32 v[246:247], v[246:247], s[100:101]
	v_rcp_f32_e32 v246, v246
	v_rcp_f32_e32 v247, v247
	s_nop 0
	v_pk_mul_f32 v[76:77], v[76:77], v[246:247]
	v_cndmask_b32_e64 v143, v166, v138, s[8:9]
	v_cndmask_b32_e64 v156, v100, v162, s[6:7]
	v_cndmask_b32_e64 v157, v101, v163, s[6:7]
	v_pk_mul_f32 v[142:143], v[124:125], v[142:143]
	v_pk_fma_f32 v[142:143], v[128:129], v[156:157], v[142:143]
	v_pk_fma_f32 v[72:73], v[72:73], v[132:133], v[142:143]
	v_pk_mul_f32 v[72:73], v[76:77], v[72:73]
	v_cvt_pk_bf16_f32 v72, v72, v73
	v_cvt_pk_bf16_f32 v73, v74, v75
	v_mov_b64_e32 v[74:75], s[30:31]
	v_mad_i64_i32 v[74:75], s[70:71], v136, s67, v[74:75]
	v_lshl_add_u64 v[74:75], v[192:193], 1, v[74:75]
	global_store_dwordx2 v[74:75], v[72:73], off
.LBB0_706:
	s_or_b64 exec, exec, s[28:29]
	s_nop 1
	v_mov_b32_dpp v72, v96 row_ror:1 row_mask:0xf bank_mask:0xf
	v_mov_b32_dpp v76, v96 row_ror:2 row_mask:0xf bank_mask:0xf
	v_mov_b32_dpp v73, v97 row_ror:1 row_mask:0xf bank_mask:0xf
	v_mov_b32_dpp v77, v97 row_ror:2 row_mask:0xf bank_mask:0xf
	v_mov_b32_dpp v74, v98 row_ror:1 row_mask:0xf bank_mask:0xf
	v_mov_b32_dpp v78, v98 row_ror:2 row_mask:0xf bank_mask:0xf
	v_mov_b32_dpp v75, v99 row_ror:1 row_mask:0xf bank_mask:0xf
	v_mov_b32_dpp v79, v99 row_ror:2 row_mask:0xf bank_mask:0xf
	v_mov_b32_dpp v88, v104 row_ror:1 row_mask:0xf bank_mask:0xf
	v_mov_b32_dpp v90, v104 row_ror:2 row_mask:0xf bank_mask:0xf
	v_mov_b32_dpp v89, v105 row_ror:1 row_mask:0xf bank_mask:0xf
	v_mov_b32_dpp v92, v105 row_ror:2 row_mask:0xf bank_mask:0xf
	v_mov_b32_dpp v91, v106 row_ror:1 row_mask:0xf bank_mask:0xf
	v_mov_b32_dpp v94, v106 row_ror:2 row_mask:0xf bank_mask:0xf
	v_mov_b32_dpp v93, v107 row_ror:1 row_mask:0xf bank_mask:0xf
	v_mov_b32_dpp v95, v107 row_ror:2 row_mask:0xf bank_mask:0xf
	v_add_u32_e32 v210, 0xb0, v200
	v_cmp_le_u32_e64 s[28:29], s46, v210
	v_add_u32_e32 v137, s41, v210
	s_and_saveexec_b64 s[46:47], s[28:29]
	s_cbranch_execz .LBB0_708
	v_cndmask_b32_e64 v78, v86, v78, s[8:9]
	v_cndmask_b32_e64 v79, v87, v79, s[8:9]
	s_waitcnt vmcnt(5)
	v_pk_mul_f32 v[78:79], v[122:123], v[78:79]
	v_cndmask_b32_e64 v74, v74, v82, s[6:7]
	v_cndmask_b32_e64 v75, v75, v83, s[6:7]
	s_waitcnt vmcnt(3)
	v_pk_fma_f32 v[74:75], v[114:115], v[74:75], v[78:79]
	v_cndmask_b32_e64 v76, v84, v76, s[8:9]
	s_waitcnt vmcnt(1)
	v_pk_fma_f32 v[74:75], v[98:99], v[118:119], v[74:75]
	v_cndmask_b32_e64 v77, v85, v77, s[8:9]
	v_pk_mul_f32 v[76:77], v[120:121], v[76:77]
	v_cndmask_b32_e64 v72, v72, v80, s[6:7]
	v_cndmask_b32_e64 v73, v73, v81, s[6:7]
	v_pk_fma_f32 v[72:73], v[112:113], v[72:73], v[76:77]
	v_pk_mul_f32 v[248:249], v[74:75], s[98:99]
	v_exp_f32_e32 v248, v248
	v_exp_f32_e32 v249, v249
	v_pk_fma_f32 v[72:73], v[96:97], v[116:117], v[72:73]
	v_cndmask_b32_e64 v142, v102, v90, s[8:9]
	v_pk_add_f32 v[248:249], v[248:249], s[100:101]
	v_rcp_f32_e32 v248, v248
	v_pk_mul_f32 v[246:247], v[72:73], s[98:99]
	v_rcp_f32_e32 v249, v249
	v_exp_f32_e32 v246, v246
	v_exp_f32_e32 v247, v247
	v_cndmask_b32_e64 v143, v138, v92, s[8:9]
	v_pk_mul_f32 v[74:75], v[74:75], v[248:249]
	v_pk_add_f32 v[246:247], v[246:247], s[100:101]
	v_rcp_f32_e32 v246, v246
	v_rcp_f32_e32 v247, v247
	s_nop 0
	v_pk_mul_f32 v[72:73], v[72:73], v[246:247]
	v_cndmask_b32_e64 v94, v140, v94, s[8:9]
	v_cndmask_b32_e64 v95, v141, v95, s[8:9]
	v_cndmask_b32_e64 v88, v88, v100, s[6:7]
	v_cndmask_b32_e64 v89, v89, v101, s[6:7]
	v_cndmask_b32_e64 v90, v91, v103, s[6:7]
	v_cndmask_b32_e64 v91, v93, v139, s[6:7]
	v_pk_mul_f32 v[92:93], v[124:125], v[142:143]
	v_pk_mul_f32 v[94:95], v[126:127], v[94:95]
	v_pk_fma_f32 v[88:89], v[128:129], v[88:89], v[92:93]
	v_pk_fma_f32 v[90:91], v[130:131], v[90:91], v[94:95]
	s_waitcnt vmcnt(0)
	v_pk_fma_f32 v[88:89], v[104:105], v[132:133], v[88:89]
	v_pk_fma_f32 v[90:91], v[106:107], v[134:135], v[90:91]
	v_pk_mul_f32 v[72:73], v[72:73], v[88:89]
	v_pk_mul_f32 v[74:75], v[74:75], v[90:91]
	v_cvt_pk_bf16_f32 v72, v72, v73
	v_cvt_pk_bf16_f32 v73, v74, v75
	v_mov_b64_e32 v[74:75], s[30:31]
	v_mad_i64_i32 v[74:75], s[70:71], v137, s67, v[74:75]
	v_lshl_add_u64 v[74:75], v[192:193], 1, v[74:75]
	global_store_dwordx2 v[74:75], v[72:73], off

.LBB0_710:
	v_mov_b32_e32 v199, v198
	v_mov_b32_e32 v104, v198
	v_mov_b32_e32 v105, v198
	v_pk_fma_f32 v[62:63], v[62:63], v[104:105], v[46:47]
	v_pk_fma_f32 v[60:61], v[60:61], v[198:199], v[44:45]
	v_pk_fma_f32 v[58:59], v[58:59], v[104:105], v[42:43]
	v_pk_fma_f32 v[56:57], v[56:57], v[198:199], v[40:41]
	s_waitcnt vmcnt(7)
	s_nop 1
	v_mov_b32_dpp v104, v60 row_ror:1 row_mask:0xf bank_mask:0xf
	v_mov_b32_dpp v112, v60 row_ror:2 row_mask:0xf bank_mask:0xf
	v_mov_b32_dpp v105, v61 row_ror:1 row_mask:0xf bank_mask:0xf
	v_mov_b32_dpp v113, v61 row_ror:2 row_mask:0xf bank_mask:0xf
	v_mov_b32_dpp v106, v62 row_ror:1 row_mask:0xf bank_mask:0xf
	v_mov_b32_dpp v114, v62 row_ror:2 row_mask:0xf bank_mask:0xf
	v_mov_b32_dpp v107, v63 row_ror:1 row_mask:0xf bank_mask:0xf
	v_mov_b32_dpp v115, v63 row_ror:2 row_mask:0xf bank_mask:0xf
	v_mov_b32_dpp v116, v56 row_ror:1 row_mask:0xf bank_mask:0xf
	v_mov_b32_dpp v118, v56 row_ror:2 row_mask:0xf bank_mask:0xf
	v_mov_b32_dpp v117, v57 row_ror:1 row_mask:0xf bank_mask:0xf
	v_mov_b32_dpp v120, v57 row_ror:2 row_mask:0xf bank_mask:0xf
	v_mov_b32_dpp v119, v58 row_ror:1 row_mask:0xf bank_mask:0xf
	v_mov_b32_dpp v122, v58 row_ror:2 row_mask:0xf bank_mask:0xf
	v_mov_b32_dpp v121, v59 row_ror:1 row_mask:0xf bank_mask:0xf
	v_mov_b32_dpp v123, v59 row_ror:2 row_mask:0xf bank_mask:0xf
	s_and_saveexec_b64 s[46:47], s[0:1]
	s_cbranch_execz .LBB0_712
	v_cndmask_b32_e64 v130, v130, v122, s[8:9]
	v_cndmask_b32_e64 v131, v131, v123, s[8:9]
	v_cndmask_b32_e64 v102, v119, v102, s[6:7]
	v_cndmask_b32_e64 v103, v121, v103, s[6:7]
	s_waitcnt vmcnt(4)
	v_pk_mul_f32 v[130:131], v[86:87], v[130:131]
	v_cndmask_b32_e64 v98, v106, v98, s[6:7]
	s_waitcnt vmcnt(2)
	v_pk_fma_f32 v[102:103], v[90:91], v[102:103], v[130:131]
	v_cndmask_b32_e64 v99, v107, v99, s[6:7]
	s_waitcnt vmcnt(0)
	v_pk_fma_f32 v[58:59], v[58:59], v[94:95], v[102:103]
	v_cndmask_b32_e64 v102, v126, v114, s[8:9]
	v_cndmask_b32_e64 v103, v127, v115, s[8:9]
	v_pk_mul_f32 v[102:103], v[78:79], v[102:103]
	v_cndmask_b32_e64 v128, v128, v118, s[8:9]
	v_pk_fma_f32 v[98:99], v[74:75], v[98:99], v[102:103]
	v_cndmask_b32_e64 v129, v129, v120, s[8:9]
	v_pk_fma_f32 v[62:63], v[62:63], v[82:83], v[98:99]
	v_cndmask_b32_e64 v100, v116, v100, s[6:7]
	v_cndmask_b32_e64 v101, v117, v101, s[6:7]
	v_pk_mul_f32 v[128:129], v[84:85], v[128:129]
	v_pk_mul_f32 v[248:249], v[62:63], s[98:99]
	v_exp_f32_e32 v248, v248
	v_pk_fma_f32 v[100:101], v[88:89], v[100:101], v[128:129]
	v_exp_f32_e32 v249, v249
	v_pk_fma_f32 v[56:57], v[56:57], v[92:93], v[100:101]
	v_cndmask_b32_e64 v100, v124, v112, s[8:9]
	v_cndmask_b32_e64 v101, v125, v113, s[8:9]
	v_pk_add_f32 v[248:249], v[248:249], s[100:101]
	v_pk_mul_f32 v[100:101], v[76:77], v[100:101]
	v_cndmask_b32_e64 v96, v104, v96, s[6:7]
	v_cndmask_b32_e64 v97, v105, v97, s[6:7]
	v_pk_fma_f32 v[96:97], v[72:73], v[96:97], v[100:101]
	v_rcp_f32_e32 v248, v248
	v_pk_fma_f32 v[60:61], v[60:61], v[80:81], v[96:97]
	v_rcp_f32_e32 v249, v249
	s_nop 0
	v_pk_mul_f32 v[62:63], v[62:63], v[248:249]
	v_pk_mul_f32 v[246:247], v[60:61], s[98:99]
	v_pk_mul_f32 v[58:59], v[62:63], v[58:59]
	v_exp_f32_e32 v246, v246
	v_exp_f32_e32 v247, v247
	s_nop 0
	v_pk_add_f32 v[246:247], v[246:247], s[100:101]
	v_rcp_f32_e32 v246, v246
	v_rcp_f32_e32 v247, v247
	s_nop 0
	v_pk_mul_f32 v[60:61], v[60:61], v[246:247]
	v_pk_mul_f32 v[56:57], v[60:61], v[56:57]
	v_cvt_pk_bf16_f32 v56, v56, v57
	v_cvt_pk_bf16_f32 v57, v58, v59
	v_mov_b64_e32 v[58:59], s[30:31]
	v_mad_i64_i32 v[58:59], s[0:1], v194, s67, v[58:59]
	v_lshl_add_u64 v[58:59], v[192:193], 1, v[58:59]
	global_store_dwordx2 v[58:59], v[56:57], off offset:8
.LBB0_712:
	s_or_b64 exec, exec, s[46:47]
	v_mov_b32_e32 v153, v152
	v_mov_b32_e32 v56, v152
	v_mov_b32_e32 v57, v152
	v_pk_fma_f32 v[54:55], v[54:55], v[56:57], v[46:47]
	v_pk_fma_f32 v[52:53], v[52:53], v[152:153], v[44:45]
	v_pk_fma_f32 v[50:51], v[50:51], v[56:57], v[42:43]
	v_pk_fma_f32 v[48:49], v[48:49], v[152:153], v[40:41]
	s_nop 1
	v_mov_b32_dpp v56, v52 row_ror:1 row_mask:0xf bank_mask:0xf
	v_mov_b32_dpp v60, v52 row_ror:2 row_mask:0xf bank_mask:0xf
	v_mov_b32_dpp v57, v53 row_ror:1 row_mask:0xf bank_mask:0xf
	v_mov_b32_dpp v61, v53 row_ror:2 row_mask:0xf bank_mask:0xf
	v_mov_b32_dpp v58, v54 row_ror:1 row_mask:0xf bank_mask:0xf
	v_mov_b32_dpp v62, v54 row_ror:2 row_mask:0xf bank_mask:0xf
	v_mov_b32_dpp v59, v55 row_ror:1 row_mask:0xf bank_mask:0xf
	v_mov_b32_dpp v63, v55 row_ror:2 row_mask:0xf bank_mask:0xf
	v_mov_b32_dpp v96, v48 row_ror:1 row_mask:0xf bank_mask:0xf
	v_mov_b32_dpp v98, v48 row_ror:2 row_mask:0xf bank_mask:0xf
	v_mov_b32_dpp v97, v49 row_ror:1 row_mask:0xf bank_mask:0xf
	v_mov_b32_dpp v100, v49 row_ror:2 row_mask:0xf bank_mask:0xf
	v_mov_b32_dpp v99, v50 row_ror:1 row_mask:0xf bank_mask:0xf
	v_mov_b32_dpp v102, v50 row_ror:2 row_mask:0xf bank_mask:0xf
	v_mov_b32_dpp v101, v51 row_ror:1 row_mask:0xf bank_mask:0xf
	v_mov_b32_dpp v103, v51 row_ror:2 row_mask:0xf bank_mask:0xf
	s_and_saveexec_b64 s[0:1], s[16:17]
	s_cbranch_execz .LBB0_714
	v_cndmask_b32_e64 v114, v114, v62, s[8:9]
	v_cndmask_b32_e64 v115, v115, v63, s[8:9]
	s_waitcnt vmcnt(5)
	v_pk_mul_f32 v[114:115], v[78:79], v[114:115]
	v_cndmask_b32_e64 v106, v58, v106, s[6:7]
	v_cndmask_b32_e64 v107, v59, v107, s[6:7]
	s_waitcnt vmcnt(3)
	v_pk_fma_f32 v[106:107], v[74:75], v[106:107], v[114:115]
	v_cndmask_b32_e64 v122, v122, v102, s[8:9]
	s_waitcnt vmcnt(1)
	v_pk_fma_f32 v[54:55], v[54:55], v[82:83], v[106:107]
	v_cndmask_b32_e64 v123, v123, v103, s[8:9]
	v_pk_mul_f32 v[248:249], v[54:55], s[98:99]
	v_cndmask_b32_e64 v112, v112, v60, s[8:9]
	v_cndmask_b32_e64 v113, v113, v61, s[8:9]
	v_exp_f32_e32 v248, v248
	v_exp_f32_e32 v249, v249
	s_nop 0
	v_pk_add_f32 v[248:249], v[248:249], s[100:101]
	v_cndmask_b32_e64 v124, v118, v98, s[8:9]
	v_cndmask_b32_e64 v118, v99, v119, s[6:7]
	v_cndmask_b32_e64 v119, v101, v121, s[6:7]
	v_pk_mul_f32 v[122:123], v[86:87], v[122:123]
	v_pk_mul_f32 v[112:113], v[76:77], v[112:113]
	v_cndmask_b32_e64 v104, v56, v104, s[6:7]
	v_cndmask_b32_e64 v105, v57, v105, s[6:7]
	v_pk_fma_f32 v[118:119], v[90:91], v[118:119], v[122:123]
	v_pk_fma_f32 v[104:105], v[72:73], v[104:105], v[112:113]
	s_waitcnt vmcnt(0)
	v_pk_fma_f32 v[50:51], v[50:51], v[94:95], v[118:119]
	v_pk_fma_f32 v[52:53], v[52:53], v[80:81], v[104:105]
	v_rcp_f32_e32 v248, v248
	v_rcp_f32_e32 v249, v249
	s_nop 0
	v_pk_mul_f32 v[54:55], v[54:55], v[248:249]
	v_pk_mul_f32 v[246:247], v[52:53], s[98:99]
	v_pk_mul_f32 v[50:51], v[54:55], v[50:51]
	v_exp_f32_e32 v246, v246
	v_exp_f32_e32 v247, v247
	v_cndmask_b32_e64 v125, v120, v100, s[8:9]
	v_pk_add_f32 v[246:247], v[246:247], s[100:101]
	v_rcp_f32_e32 v246, v246
	v_rcp_f32_e32 v247, v247
	s_nop 0
	v_pk_mul_f32 v[52:53], v[52:53], v[246:247]
	v_cndmask_b32_e64 v116, v96, v116, s[6:7]
	v_cndmask_b32_e64 v117, v97, v117, s[6:7]
	v_pk_mul_f32 v[120:121], v[84:85], v[124:125]
	v_pk_fma_f32 v[116:117], v[88:89], v[116:117], v[120:121]
	v_pk_fma_f32 v[48:49], v[48:49], v[92:93], v[116:117]
	v_pk_mul_f32 v[48:49], v[52:53], v[48:49]
	v_cvt_pk_bf16_f32 v48, v48, v49
	v_cvt_pk_bf16_f32 v49, v50, v51
	v_mov_b64_e32 v[50:51], s[30:31]
	v_mad_i64_i32 v[50:51], s[16:17], v154, s67, v[50:51]
	v_lshl_add_u64 v[50:51], v[192:193], 1, v[50:51]
	global_store_dwordx2 v[50:51], v[48:49], off offset:8
.LBB0_714:
	s_or_b64 exec, exec, s[0:1]
	v_mov_b32_e32 v145, v144
	v_mov_b32_e32 v48, v144
	v_mov_b32_e32 v49, v144
	v_pk_fma_f32 v[34:35], v[34:35], v[48:49], v[46:47]
	v_pk_fma_f32 v[32:33], v[32:33], v[144:145], v[44:45]
	v_pk_fma_f32 v[30:31], v[30:31], v[48:49], v[42:43]
	v_pk_fma_f32 v[28:29], v[28:29], v[144:145], v[40:41]
	s_nop 1
	v_mov_b32_dpp v48, v32 row_ror:1 row_mask:0xf bank_mask:0xf
	v_mov_b32_dpp v52, v32 row_ror:2 row_mask:0xf bank_mask:0xf
	v_mov_b32_dpp v49, v33 row_ror:1 row_mask:0xf bank_mask:0xf
	v_mov_b32_dpp v53, v33 row_ror:2 row_mask:0xf bank_mask:0xf
	v_mov_b32_dpp v50, v34 row_ror:1 row_mask:0xf bank_mask:0xf
	v_mov_b32_dpp v54, v34 row_ror:2 row_mask:0xf bank_mask:0xf
	v_mov_b32_dpp v51, v35 row_ror:1 row_mask:0xf bank_mask:0xf
	v_mov_b32_dpp v55, v35 row_ror:2 row_mask:0xf bank_mask:0xf
	v_mov_b32_dpp v104, v28 row_ror:1 row_mask:0xf bank_mask:0xf
	v_mov_b32_dpp v106, v28 row_ror:2 row_mask:0xf bank_mask:0xf
	v_mov_b32_dpp v105, v29 row_ror:1 row_mask:0xf bank_mask:0xf
	v_mov_b32_dpp v112, v29 row_ror:2 row_mask:0xf bank_mask:0xf
	v_mov_b32_dpp v107, v30 row_ror:1 row_mask:0xf bank_mask:0xf
	v_mov_b32_dpp v114, v30 row_ror:2 row_mask:0xf bank_mask:0xf
	v_mov_b32_dpp v113, v31 row_ror:1 row_mask:0xf bank_mask:0xf
	v_mov_b32_dpp v115, v31 row_ror:2 row_mask:0xf bank_mask:0xf
	s_and_saveexec_b64 s[0:1], s[18:19]
	s_cbranch_execz .LBB0_716
	v_cndmask_b32_e64 v62, v62, v54, s[8:9]
	v_cndmask_b32_e64 v63, v63, v55, s[8:9]
	s_waitcnt vmcnt(5)
	v_pk_mul_f32 v[62:63], v[78:79], v[62:63]
	v_cndmask_b32_e64 v58, v50, v58, s[6:7]
	v_cndmask_b32_e64 v59, v51, v59, s[6:7]
	s_waitcnt vmcnt(3)
	v_pk_fma_f32 v[58:59], v[74:75], v[58:59], v[62:63]
	v_cndmask_b32_e64 v102, v102, v114, s[8:9]
	s_waitcnt vmcnt(1)
	v_pk_fma_f32 v[34:35], v[34:35], v[82:83], v[58:59]
	v_cndmask_b32_e64 v103, v103, v115, s[8:9]
	v_pk_mul_f32 v[248:249], v[34:35], s[98:99]
	v_cndmask_b32_e64 v60, v60, v52, s[8:9]
	v_cndmask_b32_e64 v61, v61, v53, s[8:9]
	v_exp_f32_e32 v248, v248
	v_exp_f32_e32 v249, v249
	s_nop 0
	v_pk_add_f32 v[248:249], v[248:249], s[100:101]
	v_cndmask_b32_e64 v116, v98, v106, s[8:9]
	v_cndmask_b32_e64 v98, v107, v99, s[6:7]
	v_cndmask_b32_e64 v99, v113, v101, s[6:7]
	v_pk_mul_f32 v[102:103], v[86:87], v[102:103]
	v_pk_mul_f32 v[60:61], v[76:77], v[60:61]
	v_cndmask_b32_e64 v56, v48, v56, s[6:7]
	v_cndmask_b32_e64 v57, v49, v57, s[6:7]
	v_pk_fma_f32 v[98:99], v[90:91], v[98:99], v[102:103]
	v_pk_fma_f32 v[56:57], v[72:73], v[56:57], v[60:61]
	s_waitcnt vmcnt(0)
	v_pk_fma_f32 v[30:31], v[30:31], v[94:95], v[98:99]
	v_pk_fma_f32 v[32:33], v[32:33], v[80:81], v[56:57]
	v_rcp_f32_e32 v248, v248
	v_rcp_f32_e32 v249, v249
	s_nop 0
	v_pk_mul_f32 v[34:35], v[34:35], v[248:249]
	v_pk_mul_f32 v[246:247], v[32:33], s[98:99]
	v_pk_mul_f32 v[30:31], v[34:35], v[30:31]
	v_exp_f32_e32 v246, v246
	v_exp_f32_e32 v247, v247
	v_cndmask_b32_e64 v117, v100, v112, s[8:9]
	v_pk_add_f32 v[246:247], v[246:247], s[100:101]
	v_rcp_f32_e32 v246, v246
	v_rcp_f32_e32 v247, v247
	s_nop 0
	v_pk_mul_f32 v[32:33], v[32:33], v[246:247]
	v_cndmask_b32_e64 v96, v104, v96, s[6:7]
	v_cndmask_b32_e64 v97, v105, v97, s[6:7]
	v_pk_mul_f32 v[100:101], v[84:85], v[116:117]
	v_pk_fma_f32 v[96:97], v[88:89], v[96:97], v[100:101]
	v_pk_fma_f32 v[28:29], v[28:29], v[92:93], v[96:97]
	v_pk_mul_f32 v[28:29], v[32:33], v[28:29]
	v_cvt_pk_bf16_f32 v28, v28, v29
	v_cvt_pk_bf16_f32 v29, v30, v31
	v_mov_b64_e32 v[30:31], s[30:31]
	v_mad_i64_i32 v[30:31], s[16:17], v147, s67, v[30:31]
	v_lshl_add_u64 v[30:31], v[192:193], 1, v[30:31]
	global_store_dwordx2 v[30:31], v[28:29], off offset:8
.LBB0_716:
	s_or_b64 exec, exec, s[0:1]
	s_nop 1
	v_mov_b32_dpp v28, v64 row_ror:1 row_mask:0xf bank_mask:0xf
	v_mov_b32_dpp v32, v64 row_ror:2 row_mask:0xf bank_mask:0xf
	v_mov_b32_dpp v29, v65 row_ror:1 row_mask:0xf bank_mask:0xf
	v_mov_b32_dpp v33, v65 row_ror:2 row_mask:0xf bank_mask:0xf
	v_mov_b32_dpp v30, v66 row_ror:1 row_mask:0xf bank_mask:0xf
	v_mov_b32_dpp v34, v66 row_ror:2 row_mask:0xf bank_mask:0xf
	v_mov_b32_dpp v31, v67 row_ror:1 row_mask:0xf bank_mask:0xf
	v_mov_b32_dpp v35, v67 row_ror:2 row_mask:0xf bank_mask:0xf
	v_mov_b32_dpp v56, v68 row_ror:1 row_mask:0xf bank_mask:0xf
	v_mov_b32_dpp v58, v68 row_ror:2 row_mask:0xf bank_mask:0xf
	v_mov_b32_dpp v57, v69 row_ror:1 row_mask:0xf bank_mask:0xf
	v_mov_b32_dpp v60, v69 row_ror:2 row_mask:0xf bank_mask:0xf
	v_mov_b32_dpp v59, v70 row_ror:1 row_mask:0xf bank_mask:0xf
	v_mov_b32_dpp v62, v70 row_ror:2 row_mask:0xf bank_mask:0xf
	v_mov_b32_dpp v61, v71 row_ror:1 row_mask:0xf bank_mask:0xf
	v_mov_b32_dpp v63, v71 row_ror:2 row_mask:0xf bank_mask:0xf
	s_and_saveexec_b64 s[0:1], s[20:21]
	s_cbranch_execz .LBB0_718
	v_cndmask_b32_e64 v34, v54, v34, s[8:9]
	v_cndmask_b32_e64 v35, v55, v35, s[8:9]
	s_waitcnt vmcnt(5)
	v_pk_mul_f32 v[34:35], v[78:79], v[34:35]
	v_cndmask_b32_e64 v30, v30, v50, s[6:7]
	v_cndmask_b32_e64 v31, v31, v51, s[6:7]
	s_waitcnt vmcnt(3)
	v_pk_fma_f32 v[30:31], v[74:75], v[30:31], v[34:35]
	v_cndmask_b32_e64 v32, v52, v32, s[8:9]
	s_waitcnt vmcnt(1)
	v_pk_fma_f32 v[30:31], v[66:67], v[82:83], v[30:31]
	v_cndmask_b32_e64 v33, v53, v33, s[8:9]
	v_pk_mul_f32 v[32:33], v[76:77], v[32:33]
	v_cndmask_b32_e64 v28, v28, v48, s[6:7]
	v_cndmask_b32_e64 v29, v29, v49, s[6:7]
	v_pk_fma_f32 v[28:29], v[72:73], v[28:29], v[32:33]
	v_pk_mul_f32 v[248:249], v[30:31], s[98:99]
	v_exp_f32_e32 v248, v248
	v_exp_f32_e32 v249, v249
	v_pk_fma_f32 v[28:29], v[64:65], v[80:81], v[28:29]
	v_cndmask_b32_e64 v96, v106, v58, s[8:9]
	v_pk_add_f32 v[248:249], v[248:249], s[100:101]
	v_rcp_f32_e32 v248, v248
	v_pk_mul_f32 v[246:247], v[28:29], s[98:99]
	v_rcp_f32_e32 v249, v249
	v_exp_f32_e32 v246, v246
	v_exp_f32_e32 v247, v247
	v_cndmask_b32_e64 v97, v112, v60, s[8:9]
	v_pk_mul_f32 v[30:31], v[30:31], v[248:249]
	v_pk_add_f32 v[246:247], v[246:247], s[100:101]
	v_rcp_f32_e32 v246, v246
	v_rcp_f32_e32 v247, v247
	s_nop 0
	v_pk_mul_f32 v[28:29], v[28:29], v[246:247]
	v_cndmask_b32_e64 v62, v114, v62, s[8:9]
	v_cndmask_b32_e64 v63, v115, v63, s[8:9]
	v_cndmask_b32_e64 v56, v56, v104, s[6:7]
	v_cndmask_b32_e64 v57, v57, v105, s[6:7]
	v_cndmask_b32_e64 v58, v59, v107, s[6:7]
	v_cndmask_b32_e64 v59, v61, v113, s[6:7]
	v_pk_mul_f32 v[60:61], v[84:85], v[96:97]
	v_pk_mul_f32 v[62:63], v[86:87], v[62:63]
	v_pk_fma_f32 v[56:57], v[88:89], v[56:57], v[60:61]
	v_pk_fma_f32 v[58:59], v[90:91], v[58:59], v[62:63]
	s_waitcnt vmcnt(0)
	v_pk_fma_f32 v[56:57], v[68:69], v[92:93], v[56:57]
	v_pk_fma_f32 v[58:59], v[70:71], v[94:95], v[58:59]
	v_pk_mul_f32 v[28:29], v[28:29], v[56:57]
	v_pk_mul_f32 v[30:31], v[30:31], v[58:59]
	v_cvt_pk_bf16_f32 v28, v28, v29
	v_cvt_pk_bf16_f32 v29, v30, v31
	v_mov_b64_e32 v[30:31], s[30:31]
	v_mad_i64_i32 v[30:31], s[16:17], v109, s67, v[30:31]
	v_lshl_add_u64 v[30:31], v[192:193], 1, v[30:31]
	global_store_dwordx2 v[30:31], v[28:29], off offset:8
.LBB0_718:
	s_or_b64 exec, exec, s[0:1]
	v_mov_b32_e32 v109, v108
	v_mov_b32_e32 v28, v108
	v_mov_b32_e32 v29, v108
	v_pk_fma_f32 v[22:23], v[22:23], v[28:29], v[46:47]
	v_pk_fma_f32 v[20:21], v[20:21], v[108:109], v[44:45]
	v_pk_fma_f32 v[18:19], v[18:19], v[28:29], v[42:43]
	v_pk_fma_f32 v[16:17], v[16:17], v[108:109], v[40:41]
	s_nop 1
	v_mov_b32_dpp v28, v20 row_ror:1 row_mask:0xf bank_mask:0xf
	v_mov_b32_dpp v32, v20 row_ror:2 row_mask:0xf bank_mask:0xf
	v_mov_b32_dpp v29, v21 row_ror:1 row_mask:0xf bank_mask:0xf
	v_mov_b32_dpp v33, v21 row_ror:2 row_mask:0xf bank_mask:0xf
	v_mov_b32_dpp v30, v22 row_ror:1 row_mask:0xf bank_mask:0xf
	v_mov_b32_dpp v34, v22 row_ror:2 row_mask:0xf bank_mask:0xf
	v_mov_b32_dpp v31, v23 row_ror:1 row_mask:0xf bank_mask:0xf
	v_mov_b32_dpp v35, v23 row_ror:2 row_mask:0xf bank_mask:0xf
	v_mov_b32_dpp v48, v16 row_ror:1 row_mask:0xf bank_mask:0xf
	v_mov_b32_dpp v50, v16 row_ror:2 row_mask:0xf bank_mask:0xf
	v_mov_b32_dpp v49, v17 row_ror:1 row_mask:0xf bank_mask:0xf
	v_mov_b32_dpp v52, v17 row_ror:2 row_mask:0xf bank_mask:0xf
	v_mov_b32_dpp v51, v18 row_ror:1 row_mask:0xf bank_mask:0xf
	v_mov_b32_dpp v54, v18 row_ror:2 row_mask:0xf bank_mask:0xf
	v_mov_b32_dpp v53, v19 row_ror:1 row_mask:0xf bank_mask:0xf
	v_mov_b32_dpp v55, v19 row_ror:2 row_mask:0xf bank_mask:0xf
	s_and_saveexec_b64 s[0:1], s[22:23]
	s_cbranch_execz .LBB0_720
	ds_read_b128 v[56:59], v149 offset:304
	ds_read_b128 v[60:63], v149 offset:48
	ds_read_b128 v[64:67], v149 offset:16
	ds_read_b128 v[68:71], v149 offset:272
	s_waitcnt lgkmcnt(2)
	v_cndmask_b32_e64 v63, v59, v63, s[6:7]
	v_cndmask_b32_e64 v62, v58, v62, s[6:7]
	v_cndmask_b32_e64 v62, v62, v54, s[8:9]
	v_cndmask_b32_e64 v63, v63, v55, s[8:9]
	v_cndmask_b32_e64 v58, v51, v58, s[6:7]
	v_cndmask_b32_e64 v59, v53, v59, s[6:7]
	s_waitcnt vmcnt(4)
	v_pk_mul_f32 v[62:63], v[86:87], v[62:63]
	v_cndmask_b32_e64 v61, v57, v61, s[6:7]
	v_cndmask_b32_e64 v60, v56, v60, s[6:7]
	s_waitcnt vmcnt(2)
	v_pk_fma_f32 v[58:59], v[90:91], v[58:59], v[62:63]
	v_cndmask_b32_e64 v60, v60, v50, s[8:9]
	v_cndmask_b32_e64 v61, v61, v52, s[8:9]
	s_waitcnt vmcnt(0)
	v_pk_fma_f32 v[18:19], v[18:19], v[94:95], v[58:59]
	s_waitcnt lgkmcnt(0)
	v_cndmask_b32_e64 v59, v71, v67, s[6:7]
	v_cndmask_b32_e64 v58, v70, v66, s[6:7]
	v_cndmask_b32_e64 v56, v48, v56, s[6:7]
	v_cndmask_b32_e64 v57, v49, v57, s[6:7]
	v_pk_mul_f32 v[60:61], v[84:85], v[60:61]
	v_cndmask_b32_e64 v58, v58, v34, s[8:9]
	v_cndmask_b32_e64 v59, v59, v35, s[8:9]
	v_pk_fma_f32 v[56:57], v[88:89], v[56:57], v[60:61]
	v_pk_mul_f32 v[58:59], v[78:79], v[58:59]
	v_cndmask_b32_e64 v60, v30, v70, s[6:7]
	v_cndmask_b32_e64 v61, v31, v71, s[6:7]
	v_pk_fma_f32 v[58:59], v[74:75], v[60:61], v[58:59]
	v_pk_fma_f32 v[16:17], v[16:17], v[92:93], v[56:57]
	v_pk_fma_f32 v[22:23], v[22:23], v[82:83], v[58:59]
	v_cndmask_b32_e64 v57, v69, v65, s[6:7]
	v_cndmask_b32_e64 v56, v68, v64, s[6:7]
	v_cndmask_b32_e64 v56, v56, v32, s[8:9]
	v_cndmask_b32_e64 v57, v57, v33, s[8:9]
	v_pk_mul_f32 v[56:57], v[76:77], v[56:57]
	v_cndmask_b32_e64 v58, v28, v68, s[6:7]
	v_cndmask_b32_e64 v59, v29, v69, s[6:7]
	v_pk_fma_f32 v[56:57], v[72:73], v[58:59], v[56:57]
	v_pk_mul_f32 v[248:249], v[22:23], s[98:99]
	v_exp_f32_e32 v248, v248
	v_pk_fma_f32 v[20:21], v[20:21], v[80:81], v[56:57]
	v_exp_f32_e32 v249, v249
	s_nop 0
	v_pk_add_f32 v[248:249], v[248:249], s[100:101]
	v_rcp_f32_e32 v248, v248
	v_pk_mul_f32 v[246:247], v[20:21], s[98:99]
	v_rcp_f32_e32 v249, v249
	v_exp_f32_e32 v246, v246
	v_exp_f32_e32 v247, v247
	s_nop 0
	v_pk_mul_f32 v[22:23], v[22:23], v[248:249]
	s_nop 0
	v_pk_add_f32 v[246:247], v[246:247], s[100:101]
	v_rcp_f32_e32 v246, v246
	v_rcp_f32_e32 v247, v247
	s_nop 0
	v_pk_mul_f32 v[20:21], v[20:21], v[246:247]
	v_pk_mul_f32 v[18:19], v[22:23], v[18:19]
	v_pk_mul_f32 v[16:17], v[20:21], v[16:17]
	v_cvt_pk_bf16_f32 v16, v16, v17
	v_cvt_pk_bf16_f32 v17, v18, v19
	v_mov_b64_e32 v[18:19], s[30:31]
	v_mad_i64_i32 v[18:19], s[16:17], v111, s67, v[18:19]
	v_lshl_add_u64 v[18:19], v[192:193], 1, v[18:19]
	global_store_dwordx2 v[18:19], v[16:17], off offset:8
.LBB0_720:
	s_or_b64 exec, exec, s[0:1]
	v_mov_b32_e32 v147, v146
	v_mov_b32_e32 v16, v146
	v_mov_b32_e32 v17, v146
	v_pk_fma_f32 v[14:15], v[14:15], v[16:17], v[46:47]
	v_pk_fma_f32 v[12:13], v[12:13], v[146:147], v[44:45]
	v_pk_fma_f32 v[10:11], v[10:11], v[16:17], v[42:43]
	v_pk_fma_f32 v[8:9], v[8:9], v[146:147], v[40:41]
	s_nop 1
	v_mov_b32_dpp v16, v12 row_ror:1 row_mask:0xf bank_mask:0xf
	v_mov_b32_dpp v20, v12 row_ror:2 row_mask:0xf bank_mask:0xf
	v_mov_b32_dpp v17, v13 row_ror:1 row_mask:0xf bank_mask:0xf
	v_mov_b32_dpp v21, v13 row_ror:2 row_mask:0xf bank_mask:0xf
	v_mov_b32_dpp v18, v14 row_ror:1 row_mask:0xf bank_mask:0xf
	v_mov_b32_dpp v22, v14 row_ror:2 row_mask:0xf bank_mask:0xf
	v_mov_b32_dpp v19, v15 row_ror:1 row_mask:0xf bank_mask:0xf
	v_mov_b32_dpp v23, v15 row_ror:2 row_mask:0xf bank_mask:0xf
	v_mov_b32_dpp v56, v8 row_ror:1 row_mask:0xf bank_mask:0xf
	v_mov_b32_dpp v58, v8 row_ror:2 row_mask:0xf bank_mask:0xf
	v_mov_b32_dpp v57, v9 row_ror:1 row_mask:0xf bank_mask:0xf
	v_mov_b32_dpp v60, v9 row_ror:2 row_mask:0xf bank_mask:0xf
	v_mov_b32_dpp v59, v10 row_ror:1 row_mask:0xf bank_mask:0xf
	v_mov_b32_dpp v62, v10 row_ror:2 row_mask:0xf bank_mask:0xf
	v_mov_b32_dpp v61, v11 row_ror:1 row_mask:0xf bank_mask:0xf
	v_mov_b32_dpp v63, v11 row_ror:2 row_mask:0xf bank_mask:0xf
	s_and_saveexec_b64 s[0:1], s[24:25]
	s_cbranch_execz .LBB0_722
	v_cndmask_b32_e64 v34, v34, v22, s[8:9]
	v_cndmask_b32_e64 v35, v35, v23, s[8:9]
	s_waitcnt vmcnt(5)
	v_pk_mul_f32 v[34:35], v[78:79], v[34:35]
	v_cndmask_b32_e64 v30, v18, v30, s[6:7]
	v_cndmask_b32_e64 v31, v19, v31, s[6:7]
	s_waitcnt vmcnt(3)
	v_pk_fma_f32 v[30:31], v[74:75], v[30:31], v[34:35]
	v_cndmask_b32_e64 v54, v54, v62, s[8:9]
	s_waitcnt vmcnt(1)
	v_pk_fma_f32 v[14:15], v[14:15], v[82:83], v[30:31]
	v_cndmask_b32_e64 v55, v55, v63, s[8:9]
	v_pk_mul_f32 v[248:249], v[14:15], s[98:99]
	v_cndmask_b32_e64 v32, v32, v20, s[8:9]
	v_cndmask_b32_e64 v33, v33, v21, s[8:9]
	v_exp_f32_e32 v248, v248
	v_exp_f32_e32 v249, v249
	s_nop 0
	v_pk_add_f32 v[248:249], v[248:249], s[100:101]
	v_cndmask_b32_e64 v64, v50, v58, s[8:9]
	v_cndmask_b32_e64 v50, v59, v51, s[6:7]
	v_cndmask_b32_e64 v51, v61, v53, s[6:7]
	v_pk_mul_f32 v[54:55], v[86:87], v[54:55]
	v_pk_mul_f32 v[32:33], v[76:77], v[32:33]
	v_cndmask_b32_e64 v28, v16, v28, s[6:7]
	v_cndmask_b32_e64 v29, v17, v29, s[6:7]
	v_pk_fma_f32 v[50:51], v[90:91], v[50:51], v[54:55]
	v_pk_fma_f32 v[28:29], v[72:73], v[28:29], v[32:33]
	s_waitcnt vmcnt(0)
	v_pk_fma_f32 v[10:11], v[10:11], v[94:95], v[50:51]
	v_pk_fma_f32 v[12:13], v[12:13], v[80:81], v[28:29]
	v_rcp_f32_e32 v248, v248
	v_rcp_f32_e32 v249, v249
	s_nop 0
	v_pk_mul_f32 v[14:15], v[14:15], v[248:249]
	v_pk_mul_f32 v[246:247], v[12:13], s[98:99]
	v_pk_mul_f32 v[10:11], v[14:15], v[10:11]
	v_exp_f32_e32 v246, v246
	v_exp_f32_e32 v247, v247
	v_cndmask_b32_e64 v65, v52, v60, s[8:9]
	v_pk_add_f32 v[246:247], v[246:247], s[100:101]
	v_rcp_f32_e32 v246, v246
	v_rcp_f32_e32 v247, v247
	s_nop 0
	v_pk_mul_f32 v[12:13], v[12:13], v[246:247]
	v_cndmask_b32_e64 v48, v56, v48, s[6:7]
	v_cndmask_b32_e64 v49, v57, v49, s[6:7]
	v_pk_mul_f32 v[52:53], v[84:85], v[64:65]
	v_pk_fma_f32 v[48:49], v[88:89], v[48:49], v[52:53]
	v_pk_fma_f32 v[8:9], v[8:9], v[92:93], v[48:49]
	v_pk_mul_f32 v[8:9], v[12:13], v[8:9]
	v_cvt_pk_bf16_f32 v8, v8, v9
	v_cvt_pk_bf16_f32 v9, v10, v11
	v_mov_b64_e32 v[10:11], s[30:31]
	v_mad_i64_i32 v[10:11], s[16:17], v148, s67, v[10:11]
	v_lshl_add_u64 v[10:11], v[192:193], 1, v[10:11]
	global_store_dwordx2 v[10:11], v[8:9], off offset:8
.LBB0_722:
	s_or_b64 exec, exec, s[0:1]
	v_mov_b32_e32 v111, v110
	v_mov_b32_e32 v8, v110
	v_mov_b32_e32 v9, v110
	v_pk_fma_f32 v[6:7], v[6:7], v[8:9], v[46:47]
	v_pk_fma_f32 v[4:5], v[4:5], v[110:111], v[44:45]
	v_pk_fma_f32 v[2:3], v[2:3], v[8:9], v[42:43]
	v_pk_fma_f32 v[0:1], v[0:1], v[110:111], v[40:41]
	s_nop 1
	v_mov_b32_dpp v8, v4 row_ror:1 row_mask:0xf bank_mask:0xf
	v_mov_b32_dpp v12, v4 row_ror:2 row_mask:0xf bank_mask:0xf
	v_mov_b32_dpp v9, v5 row_ror:1 row_mask:0xf bank_mask:0xf
	v_mov_b32_dpp v13, v5 row_ror:2 row_mask:0xf bank_mask:0xf
	v_mov_b32_dpp v10, v6 row_ror:1 row_mask:0xf bank_mask:0xf
	v_mov_b32_dpp v14, v6 row_ror:2 row_mask:0xf bank_mask:0xf
	v_mov_b32_dpp v11, v7 row_ror:1 row_mask:0xf bank_mask:0xf
	v_mov_b32_dpp v15, v7 row_ror:2 row_mask:0xf bank_mask:0xf
	v_mov_b32_dpp v28, v0 row_ror:1 row_mask:0xf bank_mask:0xf
	v_mov_b32_dpp v32, v0 row_ror:2 row_mask:0xf bank_mask:0xf
	v_mov_b32_dpp v29, v1 row_ror:1 row_mask:0xf bank_mask:0xf
	v_mov_b32_dpp v33, v1 row_ror:2 row_mask:0xf bank_mask:0xf
	v_mov_b32_dpp v30, v2 row_ror:1 row_mask:0xf bank_mask:0xf
	v_mov_b32_dpp v34, v2 row_ror:2 row_mask:0xf bank_mask:0xf
	v_mov_b32_dpp v31, v3 row_ror:1 row_mask:0xf bank_mask:0xf
	v_mov_b32_dpp v35, v3 row_ror:2 row_mask:0xf bank_mask:0xf
	s_and_saveexec_b64 s[0:1], s[26:27]
	s_cbranch_execz .LBB0_724
	v_cndmask_b32_e64 v22, v22, v14, s[8:9]
	v_cndmask_b32_e64 v23, v23, v15, s[8:9]
	s_waitcnt vmcnt(5)
	v_pk_mul_f32 v[22:23], v[78:79], v[22:23]
	v_cndmask_b32_e64 v18, v10, v18, s[6:7]
	v_cndmask_b32_e64 v19, v11, v19, s[6:7]
	s_waitcnt vmcnt(3)
	v_pk_fma_f32 v[18:19], v[74:75], v[18:19], v[22:23]
	v_cndmask_b32_e64 v42, v62, v34, s[8:9]
	s_waitcnt vmcnt(1)
	v_pk_fma_f32 v[6:7], v[6:7], v[82:83], v[18:19]
	v_cndmask_b32_e64 v43, v63, v35, s[8:9]
	v_pk_mul_f32 v[248:249], v[6:7], s[98:99]
	v_cndmask_b32_e64 v20, v20, v12, s[8:9]
	v_cndmask_b32_e64 v21, v21, v13, s[8:9]
	v_exp_f32_e32 v248, v248
	v_exp_f32_e32 v249, v249
	s_nop 0
	v_pk_add_f32 v[248:249], v[248:249], s[100:101]
	v_cndmask_b32_e64 v46, v30, v59, s[6:7]
	v_cndmask_b32_e64 v47, v31, v61, s[6:7]
	v_pk_mul_f32 v[42:43], v[86:87], v[42:43]
	v_pk_mul_f32 v[20:21], v[76:77], v[20:21]
	v_cndmask_b32_e64 v16, v8, v16, s[6:7]
	v_cndmask_b32_e64 v17, v9, v17, s[6:7]
	v_pk_fma_f32 v[42:43], v[90:91], v[46:47], v[42:43]
	v_pk_fma_f32 v[16:17], v[72:73], v[16:17], v[20:21]
	s_waitcnt vmcnt(0)
	v_pk_fma_f32 v[2:3], v[2:3], v[94:95], v[42:43]
	v_pk_fma_f32 v[4:5], v[4:5], v[80:81], v[16:17]
	v_rcp_f32_e32 v248, v248
	v_rcp_f32_e32 v249, v249
	s_nop 0
	v_pk_mul_f32 v[6:7], v[6:7], v[248:249]
	v_pk_mul_f32 v[246:247], v[4:5], s[98:99]
	v_pk_mul_f32 v[2:3], v[6:7], v[2:3]
	v_exp_f32_e32 v246, v246
	v_exp_f32_e32 v247, v247
	v_cndmask_b32_e64 v40, v58, v32, s[8:9]
	v_pk_add_f32 v[246:247], v[246:247], s[100:101]
	v_rcp_f32_e32 v246, v246
	v_rcp_f32_e32 v247, v247
	s_nop 0
	v_pk_mul_f32 v[4:5], v[4:5], v[246:247]
	v_cndmask_b32_e64 v41, v60, v33, s[8:9]
	v_cndmask_b32_e64 v44, v28, v56, s[6:7]
	v_cndmask_b32_e64 v45, v29, v57, s[6:7]
	v_pk_mul_f32 v[40:41], v[84:85], v[40:41]
	v_pk_fma_f32 v[40:41], v[88:89], v[44:45], v[40:41]
	v_pk_fma_f32 v[0:1], v[0:1], v[92:93], v[40:41]
	v_pk_mul_f32 v[0:1], v[4:5], v[0:1]
	v_cvt_pk_bf16_f32 v0, v0, v1
	v_cvt_pk_bf16_f32 v1, v2, v3
	v_mov_b64_e32 v[2:3], s[30:31]
	v_mad_i64_i32 v[2:3], s[16:17], v136, s67, v[2:3]
	v_lshl_add_u64 v[2:3], v[192:193], 1, v[2:3]
	global_store_dwordx2 v[2:3], v[0:1], off offset:8
.LBB0_724:
	s_or_b64 exec, exec, s[0:1]
	s_nop 1
	v_mov_b32_dpp v0, v24 row_ror:1 row_mask:0xf bank_mask:0xf
	v_mov_b32_dpp v4, v24 row_ror:2 row_mask:0xf bank_mask:0xf
	v_mov_b32_dpp v1, v25 row_ror:1 row_mask:0xf bank_mask:0xf
	v_mov_b32_dpp v5, v25 row_ror:2 row_mask:0xf bank_mask:0xf
	v_mov_b32_dpp v2, v26 row_ror:1 row_mask:0xf bank_mask:0xf
	v_mov_b32_dpp v6, v26 row_ror:2 row_mask:0xf bank_mask:0xf
	v_mov_b32_dpp v3, v27 row_ror:1 row_mask:0xf bank_mask:0xf
	v_mov_b32_dpp v7, v27 row_ror:2 row_mask:0xf bank_mask:0xf
	v_mov_b32_dpp v16, v36 row_ror:1 row_mask:0xf bank_mask:0xf
	v_mov_b32_dpp v20, v36 row_ror:2 row_mask:0xf bank_mask:0xf
	v_mov_b32_dpp v17, v37 row_ror:1 row_mask:0xf bank_mask:0xf
	v_mov_b32_dpp v21, v37 row_ror:2 row_mask:0xf bank_mask:0xf
	v_mov_b32_dpp v18, v38 row_ror:1 row_mask:0xf bank_mask:0xf
	v_mov_b32_dpp v22, v38 row_ror:2 row_mask:0xf bank_mask:0xf
	v_mov_b32_dpp v19, v39 row_ror:1 row_mask:0xf bank_mask:0xf
	v_mov_b32_dpp v23, v39 row_ror:2 row_mask:0xf bank_mask:0xf
	s_and_saveexec_b64 s[0:1], s[28:29]
	s_cbranch_execz .LBB0_726
	v_cndmask_b32_e64 v6, v14, v6, s[8:9]
	v_cndmask_b32_e64 v7, v15, v7, s[8:9]
	s_waitcnt vmcnt(5)
	v_pk_mul_f32 v[6:7], v[78:79], v[6:7]
	v_cndmask_b32_e64 v2, v2, v10, s[6:7]
	v_cndmask_b32_e64 v3, v3, v11, s[6:7]
	s_waitcnt vmcnt(3)
	v_pk_fma_f32 v[2:3], v[74:75], v[2:3], v[6:7]
	v_cndmask_b32_e64 v4, v12, v4, s[8:9]
	s_waitcnt vmcnt(1)
	v_pk_fma_f32 v[2:3], v[26:27], v[82:83], v[2:3]
	v_cndmask_b32_e64 v5, v13, v5, s[8:9]
	v_pk_mul_f32 v[4:5], v[76:77], v[4:5]
	v_cndmask_b32_e64 v0, v0, v8, s[6:7]
	v_cndmask_b32_e64 v1, v1, v9, s[6:7]
	v_pk_fma_f32 v[0:1], v[72:73], v[0:1], v[4:5]
	v_pk_mul_f32 v[248:249], v[2:3], s[98:99]
	v_exp_f32_e32 v248, v248
	v_exp_f32_e32 v249, v249
	v_pk_fma_f32 v[0:1], v[24:25], v[80:81], v[0:1]
	v_cndmask_b32_e64 v20, v32, v20, s[8:9]
	v_pk_add_f32 v[248:249], v[248:249], s[100:101]
	v_rcp_f32_e32 v248, v248
	v_pk_mul_f32 v[246:247], v[0:1], s[98:99]
	v_rcp_f32_e32 v249, v249
	v_exp_f32_e32 v246, v246
	v_exp_f32_e32 v247, v247
	v_cndmask_b32_e64 v21, v33, v21, s[8:9]
	v_pk_mul_f32 v[2:3], v[2:3], v[248:249]
	v_pk_add_f32 v[246:247], v[246:247], s[100:101]
	v_rcp_f32_e32 v246, v246
	v_rcp_f32_e32 v247, v247
	s_nop 0
	v_pk_mul_f32 v[0:1], v[0:1], v[246:247]
	v_cndmask_b32_e64 v22, v34, v22, s[8:9]
	v_cndmask_b32_e64 v23, v35, v23, s[8:9]
	v_pk_mul_f32 v[20:21], v[84:85], v[20:21]
	v_pk_mul_f32 v[22:23], v[86:87], v[22:23]
	v_cndmask_b32_e64 v16, v16, v28, s[6:7]
	v_cndmask_b32_e64 v17, v17, v29, s[6:7]
	v_cndmask_b32_e64 v18, v18, v30, s[6:7]
	v_cndmask_b32_e64 v19, v19, v31, s[6:7]
	v_pk_fma_f32 v[18:19], v[90:91], v[18:19], v[22:23]
	v_pk_fma_f32 v[16:17], v[88:89], v[16:17], v[20:21]
	s_waitcnt vmcnt(0)
	v_pk_fma_f32 v[18:19], v[38:39], v[94:95], v[18:19]
	v_pk_fma_f32 v[16:17], v[36:37], v[92:93], v[16:17]
	v_pk_mul_f32 v[0:1], v[0:1], v[16:17]
	v_pk_mul_f32 v[2:3], v[2:3], v[18:19]
	v_cvt_pk_bf16_f32 v0, v0, v1
	v_cvt_pk_bf16_f32 v1, v2, v3
	v_mov_b64_e32 v[2:3], s[30:31]
	v_mad_i64_i32 v[2:3], s[16:17], v137, s67, v[2:3]
	v_lshl_add_u64 v[2:3], v[192:193], 1, v[2:3]
	global_store_dwordx2 v[2:3], v[0:1], off offset:8
